# v120 + W_in K-loop first iteration peeled with C=0 MFMAs too (all three GEMM K-loops now start without accumulator zeroing)
# speedup vs baseline: 1.0255x; 1.0086x over previous
; #define PG8_STAGE(bufoff, gbase, voff) do { _Pragma("unroll") for (int _i = 0; _i < 2; ++_i) \
;         __builtin_amdgcn_global_load_lds((const unsigned*)((const char*)(gbase) + (voff)[_i]), (PG8_LAS unsigned*)(lds + (bufoff) + ldsw + _i * 8192), 16, 0, 0); } while (0)
; #define PG8_LDA(dst, b, h) do { _Pragma("unroll") for (int m = 0; m < 4; ++m) _Pragma("unroll") for (int k = 0; k < 2; ++k) dst[m][k] = *(const PG8_LAS bf16x8*)(lds + PG8_SA(b, h) + aoff + m * 2048 + k * 1024); } while (0)
; #define PG8_LDB(dst, b, h) do { _Pragma("unroll") for (int n = 0; n < 2; ++n) _Pragma("unroll") for (int k = 0; k < 2; ++k) dst[n][k] = *(const PG8_LAS bf16x8*)(lds + PG8_SB(b, h) + boff + n * 2048 + k * 1024); } while (0)
; #define PG8_MMA(ai, bj, At, Bt) do { __builtin_amdgcn_s_setprio(1); _Pragma("unroll") for (int m = 0; m < 4; ++m) _Pragma("unroll") for (int n = 0; n < 2; ++n) _Pragma("unroll") for (int k = 0; k < 2; ++k) \
;         acc[ai][bj][m][n] = __builtin_amdgcn_mfma_f32_16x16x32_bf16(Bt[n][k], At[m][k], acc[ai][bj][m][n], 0, 0, 0); __builtin_amdgcn_s_setprio(0); } while (0)
; #define PG8_WAIT_V(n) asm volatile("s_waitcnt vmcnt(" #n ")" ::: "memory")
; #define PG8_WAIT_L(n) asm volatile("s_waitcnt lgkmcnt(" #n ")" ::: "memory")
; #define PG8_BAR __builtin_amdgcn_s_barrier()
; #define PG8_SCHED __builtin_amdgcn_sched_barrier(0)
; template <class Epi, class Sched, bool ALIGN_EPI = false, bool SP2 = false>
; __device__ __forceinline__ void gemm_phase(PG8_LAS unsigned char* lds, const Gemm g, const Sched& S, const Epi& E) {
;     ...
;         const char* nA = has_next ? (const char*)g.A + (size_t)nxt.pm * tstep : cA; const char* nB = has_next ? (const char*)g.Bt + (size_t)nxt.pn * tstep : cB;
;         for (int t = 0; t < nt; t += 2) {
;             const bool last = (t == nt - 2);
;             const char* a1 = cA + (size_t)(t + 1) * kstep;
;             const char* a2 = last ? nA : cA + (size_t)(t + 2) * kstep; const char* b2 = last ? nB : cB + (size_t)(t + 2) * kstep;
;     ...
;             PG8_LDB(B0, 0, 0); PG8_LDB(B1, 0, 1); PG8_SCHED; PG8_LDA(At, 0, 0); PG8_STAGE(PG8_SA(1, 1), a1 + hstep, voffA);
;             PG8_WAIT_V(8); PG8_WAIT_L(0); PG8_BAR; PG8_MMA(0, 0, At, B0); PG8_MMA(0, 1, At, B1); PG8_BAR; PG8_SCHED;
;             PG8_LDA(At, 0, 1); PG8_STAGE(PG8_SB(0, 0), b2, voffB); PG8_STAGE(PG8_SB(0, 1), b2 + hstep, voffB); PG8_STAGE(PG8_SA(0, 0), a2, voffA);
.LBB0_1129:
	s_ashr_i32 s79, s78, 31
	s_lshl_b64 s[22:23], s[78:79], 19
	v_readlane_b32 s5, v255, 15
	s_add_u32 s80, s5, s22
	s_addc_u32 s81, s61, s23
	s_and_b64 s[22:23], s[2:3], exec
	s_cselect_b32 s5, s81, s7
	s_cselect_b32 s9, s80, s6
	s_ashr_i32 s77, s76, 31
	s_lshl_b64 s[22:23], s[76:77], 19
	s_add_u32 s82, s55, s22
	s_addc_u32 s83, s56, s23
	s_and_b64 s[22:23], s[2:3], exec
	s_cselect_b32 s22, s83, s11
	s_cselect_b32 s23, s82, s10
	s_add_u32 s6, s6, 0xc000
	s_addc_u32 s7, s7, 0
	s_add_u32 s30, s10, 0x10000
	v_mov_b32_e32 v0, 0
	s_addc_u32 s37, s11, 0
	s_mov_b32 s40, -2
	v_add_u32_e32 v246, 0x10000, v192
	s_add_u32 s10, s6, 0x4000
	s_addc_u32 s11, s7, 0
	s_cmp_eq_u32 s40, 12
	s_cselect_b32 s86, s9, s10
	s_cselect_b32 s87, s5, s11
	s_cselect_b32 s84, s23, s30
	s_cselect_b32 s85, s22, s37
	s_add_u32 s10, s86, 0x8000
	s_addc_u32 s11, s87, 0
	s_add_i32 s77, 0, 0x10000
	s_add_i32 s79, 0, 0x14000
	ds_read_b128 v[16:19], v246
	ds_read_b128 v[20:23], v246 offset:1024
	ds_read_b128 v[24:27], v246 offset:2048
	ds_read_b128 v[32:35], v246 offset:3072
	ds_read_b128 v[48:51], v246 offset:16384
	ds_read_b128 v[52:55], v246 offset:17408
	ds_read_b128 v[56:59], v246 offset:18432
	ds_read_b128 v[60:63], v246 offset:19456
	s_add_i32 m0, s33, 0xc000
	ds_read_b128 v[160:163], v193
	ds_read_b128 v[164:167], v193 offset:1024
	ds_read_b128 v[180:183], v193 offset:2048
	ds_read_b128 v[184:187], v193 offset:3072
	ds_read_b128 v[188:191], v193 offset:4096
	ds_read_b128 v[194:197], v193 offset:5120
	ds_read_b128 v[198:201], v193 offset:6144
	ds_read_b128 v[202:205], v193 offset:7168
	global_load_lds_dwordx4 v176, s[6:7]
	s_add_i32 m0, s33, 0xe000
	s_nop 0
	global_load_lds_dwordx4 v178, s[6:7]
	s_waitcnt vmcnt(8) lgkmcnt(0)
	s_barrier
	v_mfma_f32_16x16x32_bf16 v[156:159], v[16:19], v[160:163], 0
	v_mfma_f32_16x16x32_bf16 v[152:155], v[24:27], v[160:163], 0
	v_mfma_f32_16x16x32_bf16 v[140:143], v[16:19], v[180:183], 0
	v_mfma_f32_16x16x32_bf16 v[136:139], v[24:27], v[180:183], 0
	v_mfma_f32_16x16x32_bf16 v[124:127], v[16:19], v[188:191], 0
	v_mfma_f32_16x16x32_bf16 v[120:123], v[24:27], v[188:191], 0
	v_mfma_f32_16x16x32_bf16 v[108:111], v[16:19], v[198:201], 0
	v_mfma_f32_16x16x32_bf16 v[104:107], v[24:27], v[198:201], 0
	v_mfma_f32_16x16x32_bf16 v[156:159], v[20:23], v[164:167], v[156:159]
	v_mfma_f32_16x16x32_bf16 v[152:155], v[32:35], v[164:167], v[152:155]
	v_mfma_f32_16x16x32_bf16 v[140:143], v[20:23], v[184:187], v[140:143]
	v_mfma_f32_16x16x32_bf16 v[136:139], v[32:35], v[184:187], v[136:139]
	v_mfma_f32_16x16x32_bf16 v[124:127], v[20:23], v[194:197], v[124:127]
	v_mfma_f32_16x16x32_bf16 v[120:123], v[32:35], v[194:197], v[120:123]
	v_mfma_f32_16x16x32_bf16 v[108:111], v[20:23], v[202:205], v[108:111]
	v_mfma_f32_16x16x32_bf16 v[104:107], v[32:35], v[202:205], v[104:107]
	v_mfma_f32_16x16x32_bf16 v[148:151], v[48:51], v[160:163], 0
	v_mfma_f32_16x16x32_bf16 v[144:147], v[56:59], v[160:163], 0
	v_mfma_f32_16x16x32_bf16 v[132:135], v[48:51], v[180:183], 0
	v_mfma_f32_16x16x32_bf16 v[128:131], v[56:59], v[180:183], 0
	v_mfma_f32_16x16x32_bf16 v[116:119], v[48:51], v[188:191], 0
	v_mfma_f32_16x16x32_bf16 v[112:115], v[56:59], v[188:191], 0
	v_mfma_f32_16x16x32_bf16 v[100:103], v[48:51], v[198:201], 0
	v_mfma_f32_16x16x32_bf16 v[96:99], v[56:59], v[198:201], 0
	v_mfma_f32_16x16x32_bf16 v[148:151], v[52:55], v[164:167], v[148:151]
	v_mfma_f32_16x16x32_bf16 v[144:147], v[60:63], v[164:167], v[144:147]
	v_mfma_f32_16x16x32_bf16 v[132:135], v[52:55], v[184:187], v[132:135]
	v_mfma_f32_16x16x32_bf16 v[128:131], v[60:63], v[184:187], v[128:131]
	v_mfma_f32_16x16x32_bf16 v[116:119], v[52:55], v[194:197], v[116:119]
	v_mfma_f32_16x16x32_bf16 v[112:115], v[60:63], v[194:197], v[112:115]
	v_mfma_f32_16x16x32_bf16 v[100:103], v[52:55], v[202:205], v[100:103]
	v_mfma_f32_16x16x32_bf16 v[96:99], v[60:63], v[202:205], v[96:99]
	s_barrier
	s_add_i32 s77, s77, s57
	s_mov_b32 m0, s77
	ds_read_b128 v[160:163], v193 offset:16384
	ds_read_b128 v[164:167], v193 offset:17408
	ds_read_b128 v[180:183], v193 offset:18432
	ds_read_b128 v[184:187], v193 offset:19456
	ds_read_b128 v[188:191], v193 offset:20480
	ds_read_b128 v[194:197], v193 offset:21504
	ds_read_b128 v[198:201], v193 offset:22528
	ds_read_b128 v[202:205], v193 offset:23552
	global_load_lds_dwordx4 v170, s[84:85]
	s_add_i32 m0, s77, 0x2000
	s_add_u32 s88, s84, 0x4000
	s_addc_u32 s89, s85, 0
	s_add_i32 s77, s79, s57
	global_load_lds_dwordx4 v174, s[84:85]
	s_mov_b32 m0, s77
	s_nop 0
	global_load_lds_dwordx4 v170, s[88:89]
	s_add_i32 m0, s77, 0x2000
	s_nop 0
	global_load_lds_dwordx4 v174, s[88:89]
	s_mov_b32 m0, s33
	s_nop 0
	global_load_lds_dwordx4 v168, s[86:87]
	s_mov_b32 m0, s42
	s_nop 0
	global_load_lds_dwordx4 v172, s[86:87]
	s_waitcnt vmcnt(8) lgkmcnt(0)
	s_barrier
; #define PG8_STAGE(bufoff, gbase, voff) do { _Pragma("unroll") for (int _i = 0; _i < 2; ++_i) \
;         __builtin_amdgcn_global_load_lds((const unsigned*)((const char*)(gbase) + (voff)[_i]), (PG8_LAS unsigned*)(lds + (bufoff) + ldsw + _i * 8192), 16, 0, 0); } while (0)
; #define PG8_LDA(dst, b, h) do { _Pragma("unroll") for (int m = 0; m < 4; ++m) _Pragma("unroll") for (int k = 0; k < 2; ++k) dst[m][k] = *(const PG8_LAS bf16x8*)(lds + PG8_SA(b, h) + aoff + m * 2048 + k * 1024); } while (0)
; #define PG8_LDB(dst, b, h) do { _Pragma("unroll") for (int n = 0; n < 2; ++n) _Pragma("unroll") for (int k = 0; k < 2; ++k) dst[n][k] = *(const PG8_LAS bf16x8*)(lds + PG8_SB(b, h) + boff + n * 2048 + k * 1024); } while (0)
; #define PG8_MMA(ai, bj, At, Bt) do { __builtin_amdgcn_s_setprio(1); _Pragma("unroll") for (int m = 0; m < 4; ++m) _Pragma("unroll") for (int n = 0; n < 2; ++n) _Pragma("unroll") for (int k = 0; k < 2; ++k) \
;         acc[ai][bj][m][n] = __builtin_amdgcn_mfma_f32_16x16x32_bf16(Bt[n][k], At[m][k], acc[ai][bj][m][n], 0, 0, 0); __builtin_amdgcn_s_setprio(0); } while (0)
; #define PG8_WAIT_V(n) asm volatile("s_waitcnt vmcnt(" #n ")" ::: "memory")
; #define PG8_WAIT_L(n) asm volatile("s_waitcnt lgkmcnt(" #n ")" ::: "memory")
; #define PG8_BAR __builtin_amdgcn_s_barrier()
; #define PG8_SCHED __builtin_amdgcn_sched_barrier(0)
; template <class Epi, class Sched, bool ALIGN_EPI = false, bool SP2 = false>
; __device__ __forceinline__ void gemm_phase(PG8_LAS unsigned char* lds, const Gemm g, const Sched& S, const Epi& E) {
;     ...
;             PG8_WAIT_V(8); PG8_WAIT_L(0); PG8_BAR; PG8_MMA(1, 0, At, B0); PG8_MMA(1, 1, At, B1); PG8_BAR; PG8_SCHED;
;             PG8_LDB(B0, 1, 0); PG8_LDB(B1, 1, 1); PG8_SCHED; PG8_LDA(At, 1, 0); PG8_STAGE(PG8_SA(0, 1), a2 + hstep, voffA);
;             PG8_WAIT_V(8); PG8_WAIT_L(0); PG8_BAR; PG8_MMA(0, 0, At, B0); PG8_MMA(0, 1, At, B1); PG8_BAR; PG8_SCHED;
	v_mfma_f32_16x16x32_bf16 v[92:95], v[16:19], v[160:163], 0
	v_mfma_f32_16x16x32_bf16 v[88:91], v[24:27], v[160:163], 0
	v_mfma_f32_16x16x32_bf16 v[76:79], v[16:19], v[180:183], 0
	v_mfma_f32_16x16x32_bf16 v[72:75], v[24:27], v[180:183], 0
	v_mfma_f32_16x16x32_bf16 v[44:47], v[16:19], v[188:191], 0
	v_mfma_f32_16x16x32_bf16 v[40:43], v[24:27], v[188:191], 0
	v_mfma_f32_16x16x32_bf16 v[12:15], v[16:19], v[198:201], 0
	v_mfma_f32_16x16x32_bf16 v[8:11], v[24:27], v[198:201], 0
	v_mfma_f32_16x16x32_bf16 v[92:95], v[20:23], v[164:167], v[92:95]
	v_mfma_f32_16x16x32_bf16 v[88:91], v[32:35], v[164:167], v[88:91]
	v_mfma_f32_16x16x32_bf16 v[76:79], v[20:23], v[184:187], v[76:79]
	v_mfma_f32_16x16x32_bf16 v[72:75], v[32:35], v[184:187], v[72:75]
	v_mfma_f32_16x16x32_bf16 v[44:47], v[20:23], v[194:197], v[44:47]
	v_mfma_f32_16x16x32_bf16 v[40:43], v[32:35], v[194:197], v[40:43]
	v_mfma_f32_16x16x32_bf16 v[12:15], v[20:23], v[202:205], v[12:15]
	v_mfma_f32_16x16x32_bf16 v[8:11], v[32:35], v[202:205], v[8:11]
	v_mfma_f32_16x16x32_bf16 v[36:39], v[48:51], v[188:191], 0
	v_mfma_f32_16x16x32_bf16 v[28:31], v[56:59], v[188:191], 0
	v_mfma_f32_16x16x32_bf16 v[4:7], v[48:51], v[198:201], 0
	v_mfma_f32_16x16x32_bf16 v[0:3], v[56:59], v[198:201], 0
	v_mfma_f32_16x16x32_bf16 v[16:19], v[48:51], v[160:163], 0
	v_mfma_f32_16x16x32_bf16 v[20:23], v[56:59], v[160:163], 0
	v_mfma_f32_16x16x32_bf16 v[24:27], v[48:51], v[180:183], 0
	v_mfma_f32_16x16x32_bf16 v[32:35], v[56:59], v[180:183], 0
	v_mfma_f32_16x16x32_bf16 v[36:39], v[52:55], v[194:197], v[36:39]
	v_mfma_f32_16x16x32_bf16 v[28:31], v[60:63], v[194:197], v[28:31]
	v_mfma_f32_16x16x32_bf16 v[4:7], v[52:55], v[202:205], v[4:7]
	v_mfma_f32_16x16x32_bf16 v[0:3], v[60:63], v[202:205], v[0:3]
	v_mfma_f32_16x16x32_bf16 v[16:19], v[52:55], v[164:167], v[16:19]
	v_mfma_f32_16x16x32_bf16 v[20:23], v[60:63], v[164:167], v[20:23]
	v_mfma_f32_16x16x32_bf16 v[24:27], v[52:55], v[184:187], v[24:27]
	v_mfma_f32_16x16x32_bf16 v[32:35], v[60:63], v[184:187], v[32:35]
	s_barrier
	s_add_i32 s77, 0, 0x18000
	s_add_i32 s79, 0, 0x1c000
	ds_read_b128 v[48:51], v246 offset:32768
	ds_read_b128 v[52:55], v246 offset:33792
	ds_read_b128 v[56:59], v246 offset:34816
	ds_read_b128 v[60:63], v246 offset:35840
	ds_read_b128 v[160:163], v246 offset:49152
	ds_read_b128 v[164:167], v246 offset:50176
	ds_read_b128 v[180:183], v246 offset:51200
	ds_read_b128 v[184:187], v246 offset:52224
	s_add_u32 s86, s86, 0x4000
	s_addc_u32 s87, s87, 0
	s_mov_b32 m0, s64
	ds_read_b128 v[64:67], v193 offset:32768
	ds_read_b128 v[68:71], v193 offset:33792
	ds_read_b128 v[80:83], v193 offset:34816
	ds_read_b128 v[84:87], v193 offset:35840
	ds_read_b128 v[188:191], v193 offset:36864
	ds_read_b128 v[194:197], v193 offset:37888
	ds_read_b128 v[198:201], v193 offset:38912
	ds_read_b128 v[202:205], v193 offset:39936
	global_load_lds_dwordx4 v168, s[86:87]
	s_mov_b32 m0, s65
	s_nop 0
	global_load_lds_dwordx4 v172, s[86:87]
	s_waitcnt vmcnt(8) lgkmcnt(0)
	s_barrier
	v_mfma_f32_16x16x32_bf16 v[156:159], v[48:51], v[64:67], v[156:159]
	v_mfma_f32_16x16x32_bf16 v[152:155], v[56:59], v[64:67], v[152:155]
	v_mfma_f32_16x16x32_bf16 v[140:143], v[48:51], v[80:83], v[140:143]
	v_mfma_f32_16x16x32_bf16 v[136:139], v[56:59], v[80:83], v[136:139]
	v_mfma_f32_16x16x32_bf16 v[124:127], v[48:51], v[188:191], v[124:127]
	v_mfma_f32_16x16x32_bf16 v[120:123], v[56:59], v[188:191], v[120:123]
	v_mfma_f32_16x16x32_bf16 v[108:111], v[48:51], v[198:201], v[108:111]
	v_mfma_f32_16x16x32_bf16 v[104:107], v[56:59], v[198:201], v[104:107]
	v_mfma_f32_16x16x32_bf16 v[156:159], v[52:55], v[68:71], v[156:159]
	v_mfma_f32_16x16x32_bf16 v[152:155], v[60:63], v[68:71], v[152:155]
	v_mfma_f32_16x16x32_bf16 v[140:143], v[52:55], v[84:87], v[140:143]
	v_mfma_f32_16x16x32_bf16 v[136:139], v[60:63], v[84:87], v[136:139]
	v_mfma_f32_16x16x32_bf16 v[124:127], v[52:55], v[194:197], v[124:127]
	v_mfma_f32_16x16x32_bf16 v[120:123], v[60:63], v[194:197], v[120:123]
	v_mfma_f32_16x16x32_bf16 v[108:111], v[52:55], v[202:205], v[108:111]
	v_mfma_f32_16x16x32_bf16 v[104:107], v[60:63], v[202:205], v[104:107]
	v_mfma_f32_16x16x32_bf16 v[148:151], v[160:163], v[64:67], v[148:151]
	v_mfma_f32_16x16x32_bf16 v[64:67], v[180:183], v[64:67], v[144:147]
	v_mfma_f32_16x16x32_bf16 v[144:147], v[184:187], v[68:71], v[64:67]
	v_mfma_f32_16x16x32_bf16 v[64:67], v[160:163], v[80:83], v[132:135]
	v_mfma_f32_16x16x32_bf16 v[132:135], v[164:167], v[84:87], v[64:67]
	v_mfma_f32_16x16x32_bf16 v[64:67], v[180:183], v[80:83], v[128:131]
	v_mfma_f32_16x16x32_bf16 v[128:131], v[184:187], v[84:87], v[64:67]
	v_mfma_f32_16x16x32_bf16 v[64:67], v[160:163], v[188:191], v[116:119]
	v_mfma_f32_16x16x32_bf16 v[116:119], v[164:167], v[194:197], v[64:67]
	v_mfma_f32_16x16x32_bf16 v[64:67], v[180:183], v[188:191], v[112:115]
	v_mfma_f32_16x16x32_bf16 v[112:115], v[184:187], v[194:197], v[64:67]
	v_mfma_f32_16x16x32_bf16 v[64:67], v[160:163], v[198:201], v[100:103]
	v_mfma_f32_16x16x32_bf16 v[100:103], v[164:167], v[202:205], v[64:67]
	v_mfma_f32_16x16x32_bf16 v[64:67], v[180:183], v[198:201], v[96:99]
	v_mfma_f32_16x16x32_bf16 v[148:151], v[164:167], v[68:71], v[148:151]
	v_mfma_f32_16x16x32_bf16 v[96:99], v[184:187], v[202:205], v[64:67]
	s_barrier
; #define PG8_STAGE(bufoff, gbase, voff) do { _Pragma("unroll") for (int _i = 0; _i < 2; ++_i) \
;         __builtin_amdgcn_global_load_lds((const unsigned*)((const char*)(gbase) + (voff)[_i]), (PG8_LAS unsigned*)(lds + (bufoff) + ldsw + _i * 8192), 16, 0, 0); } while (0)
; #define PG8_LDA(dst, b, h) do { _Pragma("unroll") for (int m = 0; m < 4; ++m) _Pragma("unroll") for (int k = 0; k < 2; ++k) dst[m][k] = *(const PG8_LAS bf16x8*)(lds + PG8_SA(b, h) + aoff + m * 2048 + k * 1024); } while (0)
; #define PG8_MMA(ai, bj, At, Bt) do { __builtin_amdgcn_s_setprio(1); _Pragma("unroll") for (int m = 0; m < 4; ++m) _Pragma("unroll") for (int n = 0; n < 2; ++n) _Pragma("unroll") for (int k = 0; k < 2; ++k) \
;         acc[ai][bj][m][n] = __builtin_amdgcn_mfma_f32_16x16x32_bf16(Bt[n][k], At[m][k], acc[ai][bj][m][n], 0, 0, 0); __builtin_amdgcn_s_setprio(0); } while (0)
; #define PG8_WAIT_V(n) asm volatile("s_waitcnt vmcnt(" #n ")" ::: "memory")
; #define PG8_WAIT_L(n) asm volatile("s_waitcnt lgkmcnt(" #n ")" ::: "memory")
; #define PG8_BAR __builtin_amdgcn_s_barrier()
; #define PG8_SCHED __builtin_amdgcn_sched_barrier(0)
; template <class Epi, class Sched, bool ALIGN_EPI = false, bool SP2 = false>
; __device__ __forceinline__ void gemm_phase(PG8_LAS unsigned char* lds, const Gemm g, const Sched& S, const Epi& E) {
;     ...
;             PG8_LDA(At, 1, 1); PG8_STAGE(PG8_SB(1, 0), b3, voffB); PG8_STAGE(PG8_SB(1, 1), b3 + hstep, voffB); PG8_STAGE(PG8_SA(1, 0), a3, voffA);
;             PG8_WAIT_V(8); PG8_WAIT_L(0); PG8_BAR; PG8_MMA(1, 0, At, B0); PG8_MMA(1, 1, At, B1); PG8_BAR; PG8_SCHED;
	s_add_u32 s86, s84, 0x8000
	s_addc_u32 s87, s85, 0
	s_add_i32 s77, s77, s57
	s_mov_b32 m0, s77
	ds_read_b128 v[64:67], v193 offset:49152
	ds_read_b128 v[68:71], v193 offset:50176
	ds_read_b128 v[188:191], v193 offset:51200
	ds_read_b128 v[194:197], v193 offset:52224
	ds_read_b128 v[198:201], v193 offset:53248
	ds_read_b128 v[202:205], v193 offset:54272
	ds_read_b128 v[206:209], v193 offset:55296
	ds_read_b128 v[210:213], v193 offset:56320
	global_load_lds_dwordx4 v170, s[86:87]
	s_add_i32 m0, s77, 0x2000
	s_add_u32 s84, s84, 0xc000
	s_addc_u32 s85, s85, 0
	s_add_i32 s77, s79, s57
	global_load_lds_dwordx4 v174, s[86:87]
	s_mov_b32 m0, s77
	s_nop 0
	global_load_lds_dwordx4 v170, s[84:85]
	s_add_i32 m0, s77, 0x2000
	s_nop 0
	global_load_lds_dwordx4 v174, s[84:85]
	s_mov_b32 m0, s53
	s_nop 0
	global_load_lds_dwordx4 v168, s[10:11]
	s_mov_b32 m0, s27
	s_nop 0
	global_load_lds_dwordx4 v172, s[10:11]
	s_waitcnt vmcnt(8) lgkmcnt(0)
	s_barrier
	v_mfma_f32_16x16x32_bf16 v[80:83], v[48:51], v[64:67], v[92:95]
	v_mfma_f32_16x16x32_bf16 v[92:95], v[52:55], v[68:71], v[80:83]
	v_mfma_f32_16x16x32_bf16 v[80:83], v[56:59], v[64:67], v[88:91]
	v_mfma_f32_16x16x32_bf16 v[76:79], v[48:51], v[188:191], v[76:79]
	v_mfma_f32_16x16x32_bf16 v[72:75], v[56:59], v[188:191], v[72:75]
	v_mfma_f32_16x16x32_bf16 v[44:47], v[48:51], v[198:201], v[44:47]
	v_mfma_f32_16x16x32_bf16 v[40:43], v[56:59], v[198:201], v[40:43]
	v_mfma_f32_16x16x32_bf16 v[12:15], v[48:51], v[206:209], v[12:15]
	v_mfma_f32_16x16x32_bf16 v[8:11], v[56:59], v[206:209], v[8:11]
	v_mfma_f32_16x16x32_bf16 v[88:91], v[60:63], v[68:71], v[80:83]
	v_mfma_f32_16x16x32_bf16 v[76:79], v[52:55], v[194:197], v[76:79]
	v_mfma_f32_16x16x32_bf16 v[72:75], v[60:63], v[194:197], v[72:75]
	v_mfma_f32_16x16x32_bf16 v[44:47], v[52:55], v[202:205], v[44:47]
	v_mfma_f32_16x16x32_bf16 v[40:43], v[60:63], v[202:205], v[40:43]
	v_mfma_f32_16x16x32_bf16 v[12:15], v[52:55], v[210:213], v[12:15]
	v_mfma_f32_16x16x32_bf16 v[8:11], v[60:63], v[210:213], v[8:11]
	v_mfma_f32_16x16x32_bf16 v[16:19], v[160:163], v[64:67], v[16:19]
	v_mfma_f32_16x16x32_bf16 v[84:87], v[164:167], v[68:71], v[16:19]
	v_mfma_f32_16x16x32_bf16 v[16:19], v[180:183], v[64:67], v[20:23]
	v_mfma_f32_16x16x32_bf16 v[80:83], v[184:187], v[68:71], v[16:19]
	v_mfma_f32_16x16x32_bf16 v[16:19], v[160:163], v[188:191], v[24:27]
	v_mfma_f32_16x16x32_bf16 v[68:71], v[164:167], v[194:197], v[16:19]
	v_mfma_f32_16x16x32_bf16 v[16:19], v[180:183], v[188:191], v[32:35]
	v_mfma_f32_16x16x32_bf16 v[64:67], v[184:187], v[194:197], v[16:19]
	v_mfma_f32_16x16x32_bf16 v[16:19], v[160:163], v[198:201], v[36:39]
	v_mfma_f32_16x16x32_bf16 v[36:39], v[164:167], v[202:205], v[16:19]
	v_mfma_f32_16x16x32_bf16 v[16:19], v[180:183], v[198:201], v[28:31]
	v_mfma_f32_16x16x32_bf16 v[4:7], v[160:163], v[206:209], v[4:7]
	v_mfma_f32_16x16x32_bf16 v[0:3], v[180:183], v[206:209], v[0:3]
	v_mfma_f32_16x16x32_bf16 v[28:31], v[184:187], v[202:205], v[16:19]
	v_mfma_f32_16x16x32_bf16 v[4:7], v[164:167], v[210:213], v[4:7]
	v_mfma_f32_16x16x32_bf16 v[0:3], v[184:187], v[210:213], v[0:3]
	s_barrier
	s_add_i32 s40, s40, 2
	s_add_u32 s6, s6, 0x10000
	s_addc_u32 s7, s7, 0
	s_add_u32 s30, s30, 0x10000
	s_addc_u32 s37, s37, 0
	s_cmp_gt_u32 s40, 13
